# S5 scan packed-f32 ops replaced by scalar FMAs; RWKV scan math packed (v_pk_fma_f32) with 4-way interleaved chains
# speedup vs baseline: 1.0683x; 1.0113x over previous
; DI unsigned pack2(float a, float b) { f2 v = {a, b}; bf2 c = __builtin_convertvector(v, bf2); return __builtin_bit_cast(unsigned, c); }
; DI void s5_job(const Params& p, int l, int job, char* smem) {
;     ...
;       for (int tt = 0; tt < 16; ++tt) {
;         const int t = d ? 15 - tt : tt;
;         float br = Bu[t * 128 + lane], bi = Bu[t * 128 + 64 + lane];
;         float nr = abr * xr - abi * xi + br;
;         float ni = abr * xi + abi * xr + bi;
;         xr = nr; xi = ni;
;         *(unsigned*)(Xs + t * 136 + 2 * lane) = pack2(xr, xi);
;       }
.LBB0_513:
	v_mfma_f32_16x16x32_bf16 v[106:109], v[52:55], v[16:19], 0
	v_add_u32_e32 v105, 0x400, v57
	v_lshl_add_u32 v126, s74, 9, v183
	v_lshl_add_u32 v128, s37, 9, v183
	v_mfma_f32_16x16x32_bf16 v[110:113], v[52:55], v[20:23], 0
	v_lshl_add_u32 v130, s4, 9, v183
	v_lshl_add_u32 v132, s1, 9, v183
	s_mulk_i32 s4, 0x110
	v_mfma_f32_16x16x32_bf16 v[114:117], v[52:55], v[24:27], 0
	v_add_u32_e32 v151, s4, v183
	s_nop 2
	ds_write2_b32 v57, v106, v110 offset1:16
	ds_write2_b32 v57, v107, v111 offset0:128 offset1:144
	v_mfma_f32_16x16x32_bf16 v[118:121], v[52:55], v[28:31], 0
	ds_write2_b32 v105, v108, v112 offset1:16
	ds_write2_b32 v105, v109, v113 offset0:128 offset1:144
	s_nop 5
	ds_write2_b32 v57, v114, v118 offset0:32 offset1:48
	ds_write2_b32 v57, v115, v119 offset0:160 offset1:176
	v_mfma_f32_16x16x32_bf16 v[122:125], v[52:55], v[32:35], 0
	v_lshl_add_u32 v114, s79, 9, v183
	s_mulk_i32 s79, 0x110
	v_add_u32_e32 v142, s79, v183
	v_mfma_f32_16x16x32_bf16 v[106:109], v[52:55], v[36:39], 0
	ds_write2_b32 v105, v116, v120 offset0:32 offset1:48
	ds_write2_b32 v105, v117, v121 offset0:160 offset1:176
	s_nop 5
	ds_write2_b32 v57, v122, v106 offset0:64 offset1:80
	ds_write2_b32 v57, v123, v107 offset0:192 offset1:208
	ds_write2_b32 v105, v124, v108 offset0:64 offset1:80
	ds_write2_b32 v105, v125, v109 offset0:192 offset1:208
	v_mfma_f32_16x16x32_bf16 v[110:113], v[52:55], v[40:43], 0
	v_lshl_add_u32 v106, s93, 9, v183
	v_lshl_add_u32 v108, s92, 9, v183
	s_mulk_i32 s93, 0x110
	v_mfma_f32_16x16x32_bf16 v[52:55], v[52:55], v[44:47], 0
	s_nop 7
	ds_write2_b32 v57, v110, v52 offset0:96 offset1:112
	ds_write2_b32 v57, v111, v53 offset0:224 offset1:240
	ds_write2_b32 v105, v112, v54 offset0:96 offset1:112
	ds_write2_b32 v105, v113, v55 offset0:224 offset1:240
	v_lshl_add_u32 v52, s94, 9, v183
	ds_read2st64_b32 v[52:53], v52 offset1:1
	s_mulk_i32 s94, 0x110
	ds_read2st64_b32 v[106:107], v106 offset1:1
	s_waitcnt lgkmcnt(1)
	v_fma_f32 v54, -v86, v95, v52
	v_fma_f32 v55, v86, v94, v53
	v_fma_f32 v52, v88, v94, v54
	v_fma_f32 v53, v88, v95, v55
	v_add_u32_e32 v105, s94, v183
	v_cvt_pk_bf16_f32 v54, v52, v53
	ds_write_b32 v105, v54 offset:8192
	ds_read2st64_b32 v[108:109], v108 offset1:1
	v_add_u32_e32 v138, s93, v183
	s_waitcnt lgkmcnt(2)
	v_fma_f32 v54, -v86, v53, v106
	v_fma_f32 v55, v86, v52, v107
	v_fma_f32 v52, v88, v52, v54
	v_fma_f32 v53, v88, v53, v55
	v_lshl_add_u32 v110, s86, 9, v183
	v_cvt_pk_bf16_f32 v54, v52, v53
	ds_write_b32 v138, v54 offset:8192
	s_mulk_i32 s92, 0x110
	ds_read2st64_b32 v[110:111], v110 offset1:1
	s_waitcnt lgkmcnt(2)
	v_fma_f32 v54, -v86, v53, v108
	v_fma_f32 v55, v86, v52, v109
	v_fma_f32 v52, v88, v52, v54
	v_fma_f32 v53, v88, v53, v55
	v_add_u32_e32 v139, s92, v183
	v_cvt_pk_bf16_f32 v54, v52, v53
	ds_write_b32 v139, v54 offset:8192
	v_lshl_add_u32 v112, s80, 9, v183
	s_mulk_i32 s86, 0x110
	ds_read2st64_b32 v[112:113], v112 offset1:1
	s_waitcnt lgkmcnt(2)
	v_fma_f32 v54, -v86, v53, v110
	v_fma_f32 v55, v86, v52, v111
	v_fma_f32 v52, v88, v52, v54
	v_fma_f32 v53, v88, v53, v55
	v_add_u32_e32 v140, s86, v183
	v_cvt_pk_bf16_f32 v54, v52, v53
	ds_write_b32 v140, v54 offset:8192
	s_mulk_i32 s80, 0x110
	ds_read2st64_b32 v[114:115], v114 offset1:1
	s_waitcnt lgkmcnt(2)
	v_fma_f32 v54, -v86, v53, v112
	v_fma_f32 v55, v86, v52, v113
	v_fma_f32 v52, v88, v52, v54
	v_fma_f32 v53, v88, v53, v55
	v_add_u32_e32 v141, s80, v183
	v_cvt_pk_bf16_f32 v54, v52, v53
	ds_write_b32 v141, v54 offset:8192
	v_lshl_add_u32 v116, s78, 9, v183
	ds_read2st64_b32 v[116:117], v116 offset1:1
	s_waitcnt lgkmcnt(2)
	v_fma_f32 v54, -v86, v53, v114
	v_fma_f32 v55, v86, v52, v115
	v_fma_f32 v52, v88, v52, v54
	v_fma_f32 v53, v88, v53, v55
	v_lshl_add_u32 v118, s77, 9, v183
	v_cvt_pk_bf16_f32 v54, v52, v53
	ds_write_b32 v142, v54 offset:8192
	s_mulk_i32 s78, 0x110
	ds_read2st64_b32 v[118:119], v118 offset1:1
	s_waitcnt lgkmcnt(2)
	v_fma_f32 v54, -v86, v53, v116
	v_fma_f32 v55, v86, v52, v117
	v_fma_f32 v52, v88, v52, v54
	v_fma_f32 v53, v88, v53, v55
	v_add_u32_e32 v143, s78, v183
	v_cvt_pk_bf16_f32 v54, v52, v53
	ds_write_b32 v143, v54 offset:8192
	v_lshl_add_u32 v120, s76, 9, v183
	s_mulk_i32 s77, 0x110
	ds_read2st64_b32 v[120:121], v120 offset1:1
	s_waitcnt lgkmcnt(2)
; DI u16 f2bf(float f) { unsigned u = __float_as_uint(f); u += 0x7fffu + ((u >> 16) & 1u); return (u16)(u >> 16); }
; DI float bf2f(u16 v) { return __uint_as_float(((unsigned)v) << 16); }
; DI unsigned pack2(float a, float b) { f2 v = {a, b}; bf2 c = __builtin_convertvector(v, bf2); return __builtin_bit_cast(unsigned, c); }
; DI float tanh_fast(float x) { float e = __expf(2.f * x); return 1.f - 2.f * __builtin_amdgcn_rcpf(1.f + e); }
; #define MFMA16(a, b, c) __builtin_amdgcn_mfma_f32_16x16x32_bf16((a), (b), (c), 0, 0, 0)
; #define WAVE_LDS_SYNC() do { __builtin_amdgcn_fence(__ATOMIC_RELEASE, "wavefront"); __builtin_amdgcn_wave_barrier(); __builtin_amdgcn_fence(__ATOMIC_ACQUIRE, "wavefront"); } while (0)
; DI void s5_job(const Params& p, int l, int job, char* smem) {
;     ...
;       for (int tt = 0; tt < 16; ++tt) {
;         const int t = d ? 15 - tt : tt;
;         float br = Bu[t * 128 + lane], bi = Bu[t * 128 + 64 + lane];
;         float nr = abr * xr - abi * xi + br;
;         float ni = abr * xi + abi * xr + bi;
;         xr = nr; xi = ni;
;         *(unsigned*)(Xs + t * 136 + 2 * lane) = pack2(xr, xi);
;       }
;       WAVE_LDS_SYNC();
;       f32x4 y = {0.f, 0.f, 0.f, 0.f};
; #pragma unroll
;       for (int ks = 0; ks < 4; ++ks) {
;         bf16x8 a = *(const bf16x8*)(Xs + col * 136 + 32 * ks + 8 * quad);
;         y = MFMA16(a, cf[ks], y);
;       }
; #pragma unroll
;       for (int q = 0; q < 4; ++q) {
;         const int tok = tlo + quad * 4 + q;
;         if (pass == 0) {
;           Sb[(size_t)tok * 512 + col] = f2bf(y[q]);
;         } else {
;           float u = bf2f(pu[q]);
;           float v = y[q] + bf2f(psb[q]) + dsk * u;
;           float gl = 0.5f * v * (1.f + tanh_fast(0.7978845608028654f * (v + 0.044715f * v * v * v)));
;           Pb[(size_t)tok * PW + col] = f2bf(gl);
;         }
	v_fma_f32 v54, -v86, v53, v118
	v_fma_f32 v55, v86, v52, v119
	v_fma_f32 v52, v88, v52, v54
	v_fma_f32 v53, v88, v53, v55
	v_add_u32_e32 v145, s77, v183
	v_cvt_pk_bf16_f32 v54, v52, v53
	ds_write_b32 v145, v54 offset:8192
	v_lshl_add_u32 v122, s75, 9, v183
	s_mulk_i32 s76, 0x110
	ds_read2st64_b32 v[122:123], v122 offset1:1
	s_waitcnt lgkmcnt(2)
	v_fma_f32 v54, -v86, v53, v120
	v_fma_f32 v55, v86, v52, v121
	v_fma_f32 v52, v88, v52, v54
	v_fma_f32 v53, v88, v53, v55
	v_add_u32_e32 v146, s76, v183
	v_cvt_pk_bf16_f32 v54, v52, v53
	ds_write_b32 v146, v54 offset:8192
	v_lshl_add_u32 v124, s5, 9, v183
	s_mulk_i32 s75, 0x110
	ds_read2st64_b32 v[124:125], v124 offset1:1
	s_waitcnt lgkmcnt(2)
	v_fma_f32 v54, -v86, v53, v122
	v_fma_f32 v55, v86, v52, v123
	v_fma_f32 v52, v88, v52, v54
	v_fma_f32 v53, v88, v53, v55
	v_add_u32_e32 v147, s75, v183
	v_cvt_pk_bf16_f32 v54, v52, v53
	ds_write_b32 v147, v54 offset:8192
	s_mulk_i32 s5, 0x110
	ds_read2st64_b32 v[126:127], v126 offset1:1
	s_waitcnt lgkmcnt(2)
	v_fma_f32 v54, -v86, v53, v124
	v_fma_f32 v55, v86, v52, v125
	v_fma_f32 v52, v88, v52, v54
	v_fma_f32 v53, v88, v53, v55
	v_add_u32_e32 v148, s5, v183
	v_cvt_pk_bf16_f32 v54, v52, v53
	ds_write_b32 v148, v54 offset:8192
	s_mul_i32 s5, s74, 0x110
	ds_read2st64_b32 v[128:129], v128 offset1:1
	s_waitcnt lgkmcnt(2)
	v_fma_f32 v54, -v86, v53, v126
	v_fma_f32 v55, v86, v52, v127
	v_fma_f32 v52, v88, v52, v54
	v_fma_f32 v53, v88, v53, v55
	v_add_u32_e32 v149, s5, v183
	v_cvt_pk_bf16_f32 v54, v52, v53
	ds_write_b32 v149, v54 offset:8192
	s_mul_i32 s5, s37, 0x110
	ds_read2st64_b32 v[130:131], v130 offset1:1
	s_waitcnt lgkmcnt(2)
	v_fma_f32 v54, -v86, v53, v128
	v_fma_f32 v55, v86, v52, v129
	v_fma_f32 v52, v88, v52, v54
	v_fma_f32 v53, v88, v53, v55
	v_add_u32_e32 v150, s5, v183
	v_cvt_pk_bf16_f32 v54, v52, v53
	ds_write_b32 v150, v54 offset:8192
	ds_read2st64_b32 v[132:133], v132 offset1:1
	v_lshl_add_u32 v134, s0, 9, v183
	s_waitcnt lgkmcnt(2)
	v_fma_f32 v54, -v86, v53, v130
	v_fma_f32 v55, v86, v52, v131
	v_fma_f32 v52, v88, v52, v54
	v_fma_f32 v53, v88, v53, v55
	s_mulk_i32 s1, 0x110
	v_cvt_pk_bf16_f32 v54, v52, v53
	ds_write_b32 v151, v54 offset:8192
	ds_read2st64_b32 v[134:135], v134 offset1:1
	v_add_u32_e32 v152, s1, v183
	s_waitcnt lgkmcnt(2)
	v_fma_f32 v54, -v86, v53, v132
	v_fma_f32 v55, v86, v52, v133
	v_fma_f32 v52, v88, v52, v54
	v_fma_f32 v53, v88, v53, v55
	s_mulk_i32 s0, 0x110
	v_cvt_pk_bf16_f32 v54, v52, v53
	ds_write_b32 v152, v54 offset:8192
	s_and_b64 vcc, exec, s[8:9]
	s_nop 0
	s_waitcnt lgkmcnt(1)
	v_fma_f32 v54, -v86, v53, v134
	v_fma_f32 v55, v86, v52, v135
	v_fma_f32 v94, v88, v52, v54
	v_fma_f32 v95, v88, v53, v55
	v_add_u32_e32 v53, s0, v183
	v_cvt_pk_bf16_f32 v52, v94, v95
	ds_write_b32 v53, v52 offset:8192
	ds_read_b128 v[52:55], v184 offset:8192
	ds_read_b128 v[106:109], v184 offset:8256
	s_waitcnt lgkmcnt(1)
	v_mfma_f32_16x16x32_bf16 v[52:55], v[52:55], v[0:3], 0
	ds_read_b128 v[110:113], v184 offset:8320
	s_mov_b64 s[0:1], -1
	s_waitcnt lgkmcnt(1)
	v_mfma_f32_16x16x32_bf16 v[52:55], v[106:109], v[4:7], v[52:55]
	ds_read_b128 v[106:109], v184 offset:8384
	s_waitcnt lgkmcnt(1)
	v_mfma_f32_16x16x32_bf16 v[52:55], v[110:113], v[8:11], v[52:55]
	s_waitcnt lgkmcnt(0)
	v_mfma_f32_16x16x32_bf16 v[52:55], v[106:109], v[12:15], v[52:55]
	s_cbranch_vccz .LBB0_515
	s_waitcnt vmcnt(0)
	v_lshlrev_b32_e32 v103, 16, v234
	v_lshlrev_b32_e32 v97, 16, v235
	v_lshlrev_b32_e32 v91, 16, v236
	v_lshlrev_b32_e32 v93, 16, v237
	v_lshlrev_b32_e32 v104, 16, v238
	v_lshlrev_b32_e32 v102, 16, v239
	v_lshlrev_b32_e32 v100, 16, v240
	v_lshlrev_b32_e32 v101, 16, v241
	v_add_f32_e32 v104, v104, v52
	v_fmac_f32_e32 v104, v182, v103
	v_mul_f32_e32 v105, 0x3d372713, v104
	v_mul_f32_e32 v105, v104, v105
	v_mul_f32_e32 v103, 0.5, v104
	v_fmac_f32_e32 v104, v104, v105
	v_mul_f32_e32 v104, 0x3f4c422a, v104
	v_add_f32_e32 v104, v104, v104
	v_mul_f32_e32 v104, 0x3fb8aa3b, v104
	v_exp_f32_e32 v104, v104
	s_mov_b64 s[0:1], 0
	v_add_f32_e32 v104, 1.0, v104
	v_rcp_f32_e32 v104, v104
	s_nop 0
	v_fma_f32 v104, v104, -2.0, 1.0
	v_add_f32_e32 v104, 1.0, v104
	v_mul_f32_e32 v103, v103, v104
	v_bfe_u32 v104, v103, 16, 1
	v_add3_u32 v103, v103, v104, s38
	v_mul_lo_u32 v104, v98, s81
	v_ashrrev_i32_e32 v105, 31, v104
	v_lshl_add_u64 v[104:105], v[64:65], 0, v[104:105]
	global_store_short_d16_hi v[104:105], v103, off

; DI u16 f2bf(float f) { unsigned u = __float_as_uint(f); u += 0x7fffu + ((u >> 16) & 1u); return (u16)(u >> 16); }
; DI void rwkv_job(const Params& p, int l, int job, char* smem) {
;     ...
;   bf16x8 bw[4];
;   float bias;
;   {
;     const float* W = (mm == 0 ? p.rwkv_w_up : p.rwkv_a_up) + ((size_t)(l * 2 + d) * 64) * 512 + h * 64 + nt * 32 + r;
; #pragma unroll
;     for (int ks = 0; ks < 4; ++ks)
; #pragma unroll
;       for (int jj = 0; jj < 8; ++jj) bw[ks][jj] = (short)f2bf(W[(size_t)(16 * ks + 8 * hh + jj) * 512]);
;     bias = (mm == 0 ? p.rwkv_w0 : p.rwkv_a0)[(l * 2 + d) * 512 + h * 64 + nt * 32 + r];
;   }
;   const int rp = lane >> 4, kg = lane & 15;
;   float SA[4], SB[4];
; #pragma unroll
;   for (int i = 0; i < 4; ++i) { SA[i] = 0.f; SB[i] = 0.f; }
;   const int myrow = 32 * half + 8 * wave + 2 * rp;
;   u16* ysb = p.R2 + (size_t)d * NTOK * 512 + (size_t)b * TPB * 512 + h * 64 + myrow;
;   u32x4 q_rp, q_rm, q_rn, q_kp, q_km, q_kn, q_vp, q_vm, q_vn, q_wp, q_wm, q_wn, q_ap, q_am, q_an;
.LBB0_566:
	s_or_b64 exec, exec, s[4:5]
	s_and_b32 s2, s2, 1
	s_lshl_b32 s4, s2, 5
	v_lshl_add_u32 v3, v3, 3, s4
	s_mul_hi_i32 s10, s14, 0x8800
	s_mul_i32 s11, s14, 0x8800
	s_mul_hi_i32 s4, s14, 0x2200000
	s_mul_i32 s14, s14, 0x2200000
	s_mulk_i32 s15, 0x1100
	s_add_u32 s5, s64, s14
	s_addc_u32 s12, s65, s4
	s_lshl_b32 s4, s15, 10
	v_and_b32_e32 v136, 15, v2
	v_lshrrev_b32_e32 v2, 3, v2
	s_add_u32 s4, s5, s4
	v_and_or_b32 v126, v2, 6, v3
	s_addc_u32 s5, s12, 0
	v_lshl_add_u64 v[2:3], v[4:5], 1, s[4:5]
	v_ashrrev_i32_e32 v127, 31, v126
	s_movk_i32 s4, 0x600
	v_lshl_add_u64 v[128:129], v[126:127], 1, v[2:3]
	v_mul_lo_u32 v2, v134, s4
	v_lshlrev_b32_e32 v127, 2, v91
	s_waitcnt vmcnt(25)
	v_bfe_u32 v6, v27, 16, 1
	v_bfe_u32 v7, v26, 16, 1
	v_bfe_u32 v8, v21, 16, 1
	v_bfe_u32 v9, v20, 16, 1
	v_bfe_u32 v10, v28, 16, 1
	v_bfe_u32 v11, v22, 16, 1
	v_bfe_u32 v108, v30, 16, 1
	v_or_b32_e32 v137, v127, v2
	v_mov_b32_e32 v2, 0xd200
	v_mov_b32_e32 v3, 0xc000
	v_add3_u32 v30, v30, v108, s38
	v_add3_u32 v22, v22, v11, s38
	v_add3_u32 v28, v28, v10, s38
	v_add3_u32 v20, v20, v9, s38
	v_add3_u32 v21, v21, v8, s38
	v_add3_u32 v26, v26, v7, s38
	v_add3_u32 v27, v27, v6, s38
	s_waitcnt vmcnt(21)
	v_bfe_u32 v6, v85, 16, 1
	v_bfe_u32 v7, v18, 16, 1
	v_bfe_u32 v8, v23, 16, 1
	v_bfe_u32 v9, v17, 16, 1
	v_bfe_u32 v10, v14, 16, 1
	v_bfe_u32 v11, v13, 16, 1
	v_bfe_u32 v108, v24, 16, 1
	s_movk_i32 s4, 0x90
	v_cndmask_b32_e64 v2, v2, v3, s[8:9]
	v_bfe_u32 v109, v29, 16, 1
	v_add3_u32 v24, v24, v108, s38
	v_add3_u32 v108, v13, v11, s38
	v_add3_u32 v110, v14, v10, s38
	v_add3_u32 v17, v17, v9, s38
	v_add3_u32 v23, v23, v8, s38
	v_add3_u32 v18, v18, v7, s38
	v_add3_u32 v85, v85, v6, s38
	s_waitcnt vmcnt(15)
	v_bfe_u32 v6, v76, 16, 1
	v_bfe_u32 v7, v31, 16, 1
	s_waitcnt vmcnt(13)
	v_bfe_u32 v8, v89, 16, 1
	v_bfe_u32 v9, v79, 16, 1
	v_bfe_u32 v10, v78, 16, 1
	v_bfe_u32 v11, v77, 16, 1
	v_bfe_u32 v13, v19, 16, 1
	v_bfe_u32 v14, v80, 16, 1
	v_mad_u32_u24 v132, v1, s4, v2
	v_cndmask_b32_e64 v2, v228, v233, s[8:9]
	s_add_u32 s14, s11, s15
	v_readlane_b32 s16, v254, 59
	v_add3_u32 v29, v29, v109, s38
	v_bfe_u32 v109, v15, 16, 1
	v_add3_u32 v111, v80, v14, s38
	v_add3_u32 v19, v19, v13, s38
	v_add3_u32 v112, v77, v11, s38
	v_add3_u32 v113, v78, v10, s38
	v_add3_u32 v114, v79, v9, s38
	v_add3_u32 v89, v89, v8, s38
	v_add3_u32 v31, v31, v7, s38
	v_add3_u32 v115, v76, v6, s38
	s_waitcnt vmcnt(6)
	v_bfe_u32 v6, v84, 16, 1
	v_bfe_u32 v7, v83, 16, 1
	v_bfe_u32 v8, v82, 16, 1
	v_bfe_u32 v9, v88, 16, 1
	v_bfe_u32 v10, v87, 16, 1
	v_bfe_u32 v11, v86, 16, 1
	v_bfe_u32 v13, v81, 16, 1
	v_bfe_u32 v14, v25, 16, 1
	v_mul_lo_u32 v130, v134, s4
	v_lshl_or_b32 v2, v12, 2, v2
	s_addc_u32 s15, s10, 0
	s_lshl_b32 s4, s34, 2
	v_readlane_b32 s20, v254, 63
	v_add3_u32 v109, v15, v109, s38
	v_add3_u32 v25, v25, v14, s38
	v_add3_u32 v116, v81, v13, s38
	v_add3_u32 v117, v86, v11, s38
	v_add3_u32 v118, v87, v10, s38
	v_add3_u32 v88, v88, v9, s38
	v_add3_u32 v119, v82, v8, s38
	v_add3_u32 v121, v83, v7, s38
	v_add3_u32 v125, v84, v6, s38
	v_lshlrev_b32_e32 v131, 4, v90
	v_lshlrev_b32_e32 v133, 4, v16
	v_lshl_add_u32 v145, v1, 2, v2
	v_or_b32_e32 v1, s2, v90
	v_lshlrev_b32_e32 v139, 4, v136
	v_lshlrev_b32_e32 v140, 2, v126
	v_mul_u32_u24_e32 v16, 0x1800, v16
	v_readlane_b32 s21, v255, 0
	s_add_u32 s34, s20, s4
	s_mov_b32 s2, 0
	v_cmp_eq_u32_e64 s[8:9], 0, v1
	v_lshlrev_b32_e32 v138, 2, v136
	s_waitcnt vmcnt(5)
	v_mov_b32_e32 v1, v0
	v_mov_b32_e32 v2, v0
	v_mov_b32_e32 v3, v0
	v_mov_b32_e32 v4, v0
	v_mov_b32_e32 v5, v0
	v_mov_b32_e32 v6, v0
	v_mov_b32_e32 v7, v0
	v_mov_b32_e32 v8, v0
	v_mov_b32_e32 v9, v0
	v_mov_b32_e32 v10, v0
	v_mov_b32_e32 v11, v0
	v_mov_b32_e32 v12, v0
	v_mov_b32_e32 v13, v0
	v_mov_b32_e32 v14, v0
	v_mov_b32_e32 v15, v0
	v_perm_b32 v79, v27, v26, s87
	v_perm_b32 v78, v21, v20, s87
	v_perm_b32 v77, v28, v22, s87
	v_perm_b32 v76, v30, v29, s87
	v_perm_b32 v83, v85, v18, s87
	v_perm_b32 v82, v23, v17, s87
	v_perm_b32 v81, v110, v108, s87
	v_perm_b32 v80, v24, v109, s87
	v_perm_b32 v87, v115, v31, s87
	v_perm_b32 v86, v89, v114, s87
	v_perm_b32 v85, v113, v112, s87
	v_perm_b32 v84, v19, v111, s87
	v_perm_b32 v91, v125, v121, s87
	v_perm_b32 v90, v119, v88, s87
	v_perm_b32 v89, v118, v117, s87
	v_perm_b32 v88, v116, v25, s87
	s_addc_u32 s35, s21, 0
	v_and_b32_e32 v141, 3, v136
	v_lshrrev_b32_e32 v142, 2, v136
	v_lshl_add_u32 v141, v141, 2, v142
	v_sub_u32_e32 v142, 0x120b, v141
	v_add_u32_e32 v141, -12, v141
	v_or_b32_e32 v143, 0x600, v139
	v_add_u32_e32 v148, 0xb00, v140
	v_add_u32_e32 v149, v130, v131
	v_add_u32_e32 v150, v132, v133
	v_add_u32_e32 v151, v145, v16
	v_mov_b32_e32 v152, 0
	v_mov_b32_e32 v153, 0
	v_mov_b32_e32 v154, 0
	v_mov_b32_e32 v155, 0
	v_mov_b32_e32 v156, 0
	v_mov_b32_e32 v157, 0
	v_mov_b32_e32 v158, 0
	v_mov_b32_e32 v198, 0
	v_mov_b32_e32 v199, 0
	v_mov_b32_e32 v200, 0
	v_mov_b32_e32 v201, 0
	v_mov_b32_e32 v202, 0
	v_mov_b32_e32 v203, 0
	v_mov_b32_e32 v204, 0
	v_mov_b32_e32 v205, 0
	s_waitcnt lgkmcnt(0)
	s_barrier
	v_readlane_b32 s17, v254, 60
	v_readlane_b32 s18, v254, 61
	v_readlane_b32 s19, v254, 62
	v_readlane_b32 s22, v255, 1
	v_readlane_b32 s23, v255, 2
	v_readlane_b32 s24, v255, 3
	v_readlane_b32 s25, v255, 4
	v_readlane_b32 s26, v255, 5
	v_readlane_b32 s27, v255, 6
	v_readlane_b32 s28, v255, 7
	v_readlane_b32 s29, v255, 8
	v_readlane_b32 s30, v255, 9
	v_readlane_b32 s31, v255, 10
	s_branch .LBB0_568

; DI void rwkv_job(const Params& p, int l, int job, char* smem) {
;     ...
;     {
;       float4 Ar0, Aw0, Ad0, An0, Aa0, Br0, Bw0, Bd0, Bn0, Ba0;
;       float2 Avv, Bvv;
;       float ykeep0 = 0.f, ykeep1 = 0.f;
;       RW_LDOPS(A, 0)
.LBB0_596:
	s_waitcnt lgkmcnt(0)
	s_barrier
	ds_read_b128 v[108:111], v139 offset:768
	ds_read_b64 v[112:113], v140 offset:1280
	ds_read_b128 v[24:27], v139 offset:512
	ds_read_b128 v[28:31], v139 offset:1024
	ds_read_b128 v[20:23], v139 offset:256
	ds_read_b128 v[16:19], v139
	ds_read_b128 v[168:171], v143 offset:768
	ds_read_b64 v[172:173], v148
	ds_read_b128 v[164:167], v143 offset:512
	ds_read_b128 v[176:179], v143 offset:1024
	ds_read_b128 v[160:163], v143 offset:256
	ds_read_b128 v[212:215], v143
	v_mov_b32_e32 v117, 0
	s_mov_b32 s2, 0
	s_movk_i32 s4, 0x600
	v_mov_b32_e32 v114, v148
	v_mov_b32_e32 v115, v143
	v_mov_b32_e32 v116, v142
	v_mov_b32_e32 v118, 0
	s_branch .LBB0_598

; DI void rwkv_job(const Params& p, int l, int job, char* smem) {
;     ...
; #pragma unroll 1
;       for (int st = 0; st < RC; st += 4) {
;         RW_LDOPS(B, st + 1)
;         RW_STEP(A, st, 0)
;         RW_LDOPS(A, st + 2)
;         RW_STEP(B, st + 1, 0)
;         RW_LDOPS(B, st + 3)
;         RW_STEP(A, st + 2, 0)
;         const int sn = st + 4 < RC ? st + 4 : RC - 1;
;         RW_LDOPS(A, sn)
;         RW_STEP(B, st + 3, 1)
;       }
.LBB0_598:
	s_waitcnt lgkmcnt(7)
	v_pk_mul_f32 v[182:183], v[198:199], v[108:109]
	v_pk_mul_f32 v[184:185], v[202:203], v[108:109]
	s_cmp_gt_u32 s2, 27
	v_pk_fma_f32 v[182:183], v[200:201], v[110:111], v[182:183]
	v_pk_fma_f32 v[184:185], v[204:205], v[110:111], v[184:185]
	s_cselect_b64 s[10:11], -1, 0
	v_add_f32_e32 v180, v182, v183
	v_add_f32_e32 v181, v184, v185
	v_pk_mul_f32 v[208:209], v[112:113], v[24:25] op_sel_hi:[0,1]
	v_add_f32_dpp v180, v180, v180 quad_perm:[1,0,3,2] row_mask:0xf bank_mask:0xf bound_ctrl:1
	v_add_f32_dpp v181, v181, v181 quad_perm:[1,0,3,2] row_mask:0xf bank_mask:0xf bound_ctrl:1
	v_pk_mul_f32 v[210:211], v[112:113], v[24:25] op_sel:[1,0] op_sel_hi:[1,1]
	v_add_f32_dpp v180, v180, v180 quad_perm:[2,3,0,1] row_mask:0xf bank_mask:0xf bound_ctrl:1
	v_add_f32_dpp v181, v181, v181 quad_perm:[2,3,0,1] row_mask:0xf bank_mask:0xf bound_ctrl:1
	v_pk_mul_f32 v[130:131], v[112:113], v[26:27] op_sel_hi:[0,1]
	v_add_f32_dpp v180, v180, v180 row_half_mirror row_mask:0xf bank_mask:0xf bound_ctrl:1
	v_add_f32_dpp v181, v181, v181 row_half_mirror row_mask:0xf bank_mask:0xf bound_ctrl:1
	v_pk_mul_f32 v[132:133], v[112:113], v[26:27] op_sel:[1,0] op_sel_hi:[1,1]
	v_add_f32_dpp v180, v180, v180 row_mirror row_mask:0xf bank_mask:0xf bound_ctrl:1
	v_add_f32_dpp v181, v181, v181 row_mirror row_mask:0xf bank_mask:0xf bound_ctrl:1
	v_pk_fma_f32 v[208:209], v[180:181], v[28:29], v[208:209] op_sel_hi:[0,1,1]
	v_pk_fma_f32 v[210:211], v[180:181], v[28:29], v[210:211] op_sel:[1,0,0] op_sel_hi:[1,1,1]
	v_pk_fma_f32 v[130:131], v[180:181], v[30:31], v[130:131] op_sel_hi:[0,1,1]
	v_pk_fma_f32 v[132:133], v[180:181], v[30:31], v[132:133] op_sel:[1,0,0] op_sel_hi:[1,1,1]
	v_pk_fma_f32 v[198:199], v[198:199], v[20:21], v[208:209]
	v_pk_fma_f32 v[202:203], v[202:203], v[20:21], v[210:211]
	v_pk_fma_f32 v[200:201], v[200:201], v[22:23], v[130:131]
	v_pk_fma_f32 v[204:205], v[204:205], v[22:23], v[132:133]
	ds_read_b128 v[108:111], v115 offset:2304
	ds_read_b64 v[112:113], v114 offset:1536
	ds_read_b128 v[24:27], v115 offset:2048
	ds_read_b128 v[28:31], v115 offset:2560
	ds_read_b128 v[20:23], v115 offset:1792
	s_waitcnt lgkmcnt(11)
	s_waitcnt lgkmcnt(6)
	v_pk_mul_f32 v[182:183], v[198:199], v[168:169]
	v_pk_mul_f32 v[184:185], v[202:203], v[168:169]
	v_pk_mul_f32 v[186:187], v[198:199], v[16:17]
	v_pk_mul_f32 v[188:189], v[202:203], v[16:17]
	v_pk_fma_f32 v[182:183], v[200:201], v[170:171], v[182:183]
	v_pk_fma_f32 v[184:185], v[204:205], v[170:171], v[184:185]
	v_pk_fma_f32 v[186:187], v[200:201], v[18:19], v[186:187]
	v_pk_fma_f32 v[188:189], v[204:205], v[18:19], v[188:189]
	v_add_f32_e32 v180, v182, v183
	v_add_f32_e32 v181, v184, v185
	v_add_f32_e32 v146, v186, v187
	v_add_f32_e32 v147, v188, v189
	ds_read_b128 v[16:19], v115 offset:1536
	v_pk_mul_f32 v[208:209], v[172:173], v[164:165] op_sel_hi:[0,1]
	v_add_f32_dpp v180, v180, v180 quad_perm:[1,0,3,2] row_mask:0xf bank_mask:0xf bound_ctrl:1
	v_add_f32_dpp v181, v181, v181 quad_perm:[1,0,3,2] row_mask:0xf bank_mask:0xf bound_ctrl:1
	v_pk_mul_f32 v[210:211], v[172:173], v[164:165] op_sel:[1,0] op_sel_hi:[1,1]
	v_add_f32_dpp v180, v180, v180 quad_perm:[2,3,0,1] row_mask:0xf bank_mask:0xf bound_ctrl:1
	v_add_f32_dpp v181, v181, v181 quad_perm:[2,3,0,1] row_mask:0xf bank_mask:0xf bound_ctrl:1
	v_pk_mul_f32 v[130:131], v[172:173], v[166:167] op_sel_hi:[0,1]
	v_add_f32_dpp v180, v180, v180 row_half_mirror row_mask:0xf bank_mask:0xf bound_ctrl:1
	v_add_f32_dpp v181, v181, v181 row_half_mirror row_mask:0xf bank_mask:0xf bound_ctrl:1
	v_pk_mul_f32 v[132:133], v[172:173], v[166:167] op_sel:[1,0] op_sel_hi:[1,1]
	v_add_f32_dpp v180, v180, v180 row_mirror row_mask:0xf bank_mask:0xf bound_ctrl:1
	v_add_f32_dpp v181, v181, v181 row_mirror row_mask:0xf bank_mask:0xf bound_ctrl:1
	v_pk_fma_f32 v[208:209], v[180:181], v[176:177], v[208:209] op_sel_hi:[0,1,1]
	v_pk_fma_f32 v[210:211], v[180:181], v[176:177], v[210:211] op_sel:[1,0,0] op_sel_hi:[1,1,1]
	v_pk_fma_f32 v[130:131], v[180:181], v[178:179], v[130:131] op_sel_hi:[0,1,1]
	v_pk_fma_f32 v[132:133], v[180:181], v[178:179], v[132:133] op_sel:[1,0,0] op_sel_hi:[1,1,1]
	v_pk_fma_f32 v[198:199], v[198:199], v[160:161], v[208:209]
	v_pk_fma_f32 v[202:203], v[202:203], v[160:161], v[210:211]
	v_pk_fma_f32 v[200:201], v[200:201], v[162:163], v[130:131]
	v_pk_fma_f32 v[204:205], v[204:205], v[162:163], v[132:133]
	ds_read_b128 v[168:171], v115 offset:3840
	ds_read_b64 v[172:173], v114 offset:3072
	ds_read_b128 v[164:167], v115 offset:3584
	ds_read_b128 v[176:179], v115 offset:4096
	ds_read_b128 v[160:163], v115 offset:3328
	s_waitcnt lgkmcnt(11)
	s_waitcnt lgkmcnt(6)
; DI void rwkv_job(const Params& p, int l, int job, char* smem) {
;     ...
; #pragma unroll 1
;       for (int st = 0; st < RC; st += 4) {
;         RW_LDOPS(B, st + 1)
;         RW_STEP(A, st, 0)
;         RW_LDOPS(A, st + 2)
;         RW_STEP(B, st + 1, 0)
;         RW_LDOPS(B, st + 3)
;         RW_STEP(A, st + 2, 0)
;         const int sn = st + 4 < RC ? st + 4 : RC - 1;
;         RW_LDOPS(A, sn)
;         RW_STEP(B, st + 3, 1)
;       }
	v_pk_mul_f32 v[182:183], v[198:199], v[108:109]
	v_pk_mul_f32 v[184:185], v[202:203], v[108:109]
	v_pk_mul_f32 v[186:187], v[198:199], v[212:213]
	v_pk_mul_f32 v[188:189], v[202:203], v[212:213]
	v_pk_fma_f32 v[182:183], v[200:201], v[110:111], v[182:183]
	v_pk_fma_f32 v[184:185], v[204:205], v[110:111], v[184:185]
	v_pk_fma_f32 v[186:187], v[200:201], v[214:215], v[186:187]
	v_pk_fma_f32 v[188:189], v[204:205], v[214:215], v[188:189]
	v_add_f32_e32 v180, v182, v183
	v_add_f32_e32 v181, v184, v185
	v_add_f32_e32 v190, v186, v187
	v_add_f32_e32 v191, v188, v189
	ds_read_b128 v[212:215], v115 offset:3072
	v_pk_mul_f32 v[208:209], v[112:113], v[24:25] op_sel_hi:[0,1]
	v_add_f32_dpp v180, v180, v180 quad_perm:[1,0,3,2] row_mask:0xf bank_mask:0xf bound_ctrl:1
	v_add_f32_dpp v181, v181, v181 quad_perm:[1,0,3,2] row_mask:0xf bank_mask:0xf bound_ctrl:1
	v_pk_mul_f32 v[210:211], v[112:113], v[24:25] op_sel:[1,0] op_sel_hi:[1,1]
	v_add_f32_dpp v180, v180, v180 quad_perm:[2,3,0,1] row_mask:0xf bank_mask:0xf bound_ctrl:1
	v_add_f32_dpp v181, v181, v181 quad_perm:[2,3,0,1] row_mask:0xf bank_mask:0xf bound_ctrl:1
	v_pk_mul_f32 v[130:131], v[112:113], v[26:27] op_sel_hi:[0,1]
	v_add_f32_dpp v180, v180, v180 row_half_mirror row_mask:0xf bank_mask:0xf bound_ctrl:1
	v_add_f32_dpp v181, v181, v181 row_half_mirror row_mask:0xf bank_mask:0xf bound_ctrl:1
	v_pk_mul_f32 v[132:133], v[112:113], v[26:27] op_sel:[1,0] op_sel_hi:[1,1]
	v_add_f32_dpp v180, v180, v180 row_mirror row_mask:0xf bank_mask:0xf bound_ctrl:1
	v_add_f32_dpp v181, v181, v181 row_mirror row_mask:0xf bank_mask:0xf bound_ctrl:1
	v_pk_fma_f32 v[208:209], v[180:181], v[28:29], v[208:209] op_sel_hi:[0,1,1]
	v_pk_fma_f32 v[210:211], v[180:181], v[28:29], v[210:211] op_sel:[1,0,0] op_sel_hi:[1,1,1]
	v_pk_fma_f32 v[130:131], v[180:181], v[30:31], v[130:131] op_sel_hi:[0,1,1]
	v_pk_fma_f32 v[132:133], v[180:181], v[30:31], v[132:133] op_sel:[1,0,0] op_sel_hi:[1,1,1]
	v_pk_fma_f32 v[198:199], v[198:199], v[20:21], v[208:209]
	v_pk_fma_f32 v[202:203], v[202:203], v[20:21], v[210:211]
	v_pk_fma_f32 v[200:201], v[200:201], v[22:23], v[130:131]
	v_pk_fma_f32 v[204:205], v[204:205], v[22:23], v[132:133]
	ds_read_b128 v[108:111], v115 offset:5376
	ds_read_b64 v[112:113], v114 offset:4608
	ds_read_b128 v[24:27], v115 offset:5120
	ds_read_b128 v[28:31], v115 offset:5632
	ds_read_b128 v[20:23], v115 offset:4864
	s_waitcnt lgkmcnt(11)
	s_waitcnt lgkmcnt(6)
	v_pk_mul_f32 v[182:183], v[198:199], v[168:169]
	v_pk_mul_f32 v[184:185], v[202:203], v[168:169]
	v_pk_mul_f32 v[186:187], v[198:199], v[16:17]
	v_pk_mul_f32 v[188:189], v[202:203], v[16:17]
	v_pk_fma_f32 v[182:183], v[200:201], v[170:171], v[182:183]
	v_pk_fma_f32 v[184:185], v[204:205], v[170:171], v[184:185]
	v_pk_fma_f32 v[186:187], v[200:201], v[18:19], v[186:187]
	v_pk_fma_f32 v[188:189], v[204:205], v[18:19], v[188:189]
	v_add_f32_e32 v180, v182, v183
	v_add_f32_e32 v181, v184, v185
	v_add_f32_e32 v192, v186, v187
	v_add_f32_e32 v193, v188, v189
	ds_read_b128 v[16:19], v115 offset:4608
	v_pk_mul_f32 v[208:209], v[172:173], v[164:165] op_sel_hi:[0,1]
	v_add_f32_dpp v180, v180, v180 quad_perm:[1,0,3,2] row_mask:0xf bank_mask:0xf bound_ctrl:1
	v_add_f32_dpp v181, v181, v181 quad_perm:[1,0,3,2] row_mask:0xf bank_mask:0xf bound_ctrl:1
	v_pk_mul_f32 v[210:211], v[172:173], v[164:165] op_sel:[1,0] op_sel_hi:[1,1]
	v_add_f32_dpp v180, v180, v180 quad_perm:[2,3,0,1] row_mask:0xf bank_mask:0xf bound_ctrl:1
	v_add_f32_dpp v181, v181, v181 quad_perm:[2,3,0,1] row_mask:0xf bank_mask:0xf bound_ctrl:1
	v_pk_mul_f32 v[130:131], v[172:173], v[166:167] op_sel_hi:[0,1]
	v_add_f32_dpp v180, v180, v180 row_half_mirror row_mask:0xf bank_mask:0xf bound_ctrl:1
	v_add_f32_dpp v181, v181, v181 row_half_mirror row_mask:0xf bank_mask:0xf bound_ctrl:1
	v_pk_mul_f32 v[132:133], v[172:173], v[166:167] op_sel:[1,0] op_sel_hi:[1,1]
	v_add_f32_dpp v180, v180, v180 row_mirror row_mask:0xf bank_mask:0xf bound_ctrl:1
	v_add_f32_dpp v181, v181, v181 row_mirror row_mask:0xf bank_mask:0xf bound_ctrl:1
	v_pk_fma_f32 v[208:209], v[180:181], v[176:177], v[208:209] op_sel_hi:[0,1,1]
	v_pk_fma_f32 v[210:211], v[180:181], v[176:177], v[210:211] op_sel:[1,0,0] op_sel_hi:[1,1,1]
	v_pk_fma_f32 v[130:131], v[180:181], v[178:179], v[130:131] op_sel_hi:[0,1,1]
	v_pk_fma_f32 v[132:133], v[180:181], v[178:179], v[132:133] op_sel:[1,0,0] op_sel_hi:[1,1,1]
	v_pk_fma_f32 v[198:199], v[198:199], v[160:161], v[208:209]
	v_pk_fma_f32 v[202:203], v[202:203], v[160:161], v[210:211]
	v_pk_fma_f32 v[200:201], v[200:201], v[162:163], v[130:131]
	v_pk_fma_f32 v[204:205], v[204:205], v[162:163], v[132:133]
	ds_read_b128 v[168:171], v115 offset:6912
	ds_read_b64 v[172:173], v114 offset:6144
	ds_read_b128 v[164:167], v115 offset:6656
	ds_read_b128 v[176:179], v115 offset:7168
	ds_read_b128 v[160:163], v115 offset:6400
	s_waitcnt lgkmcnt(11)
	v_pk_mul_f32 v[186:187], v[198:199], v[212:213]
	v_pk_mul_f32 v[188:189], v[202:203], v[212:213]
	s_bfe_u32 s37, s2, 0x20002
	v_pk_fma_f32 v[186:187], v[200:201], v[214:215], v[186:187]
	v_pk_fma_f32 v[188:189], v[204:205], v[214:215], v[188:189]
	v_add_f32_dpp v146, v146, v146 row_ror:8 row_mask:0xf bank_mask:0x3 bound_ctrl:1
	v_add_f32_e32 v206, v186, v187
	v_add_f32_e32 v207, v188, v189
	ds_read_b128 v[212:215], v115 offset:6144
	v_add_f32_dpp v147, v147, v147 row_ror:8 row_mask:0xf bank_mask:0x3 bound_ctrl:1
	v_add_f32_dpp v190, v190, v190 row_ror:8 row_mask:0xf bank_mask:0x3 bound_ctrl:1
	v_add_f32_dpp v191, v191, v191 row_ror:8 row_mask:0xf bank_mask:0x3 bound_ctrl:1
	v_add_f32_dpp v146, v192, v192 row_ror:8 row_mask:0xf bank_mask:0xc bound_ctrl:1
	v_add_f32_dpp v147, v193, v193 row_ror:8 row_mask:0xf bank_mask:0xc bound_ctrl:1
	v_add_f32_dpp v190, v206, v206 row_ror:8 row_mask:0xf bank_mask:0xc bound_ctrl:1
	v_add_f32_dpp v191, v207, v207 row_ror:8 row_mask:0xf bank_mask:0xc bound_ctrl:1
	v_add_f32_dpp v146, v146, v146 row_half_mirror row_mask:0xf bank_mask:0x5 bound_ctrl:1
	v_add_f32_dpp v147, v147, v147 row_half_mirror row_mask:0xf bank_mask:0x5 bound_ctrl:1
	v_add_f32_dpp v146, v190, v190 row_half_mirror row_mask:0xf bank_mask:0xa bound_ctrl:1
	v_add_f32_dpp v147, v191, v191 row_half_mirror row_mask:0xf bank_mask:0xa bound_ctrl:1
	s_lshl_b32 s12, 0x11111111, s37
	v_add_f32_dpp v146, v146, v146 quad_perm:[1,0,3,2] row_mask:0xf bank_mask:0xf bound_ctrl:1
	v_add_f32_dpp v147, v147, v147 quad_perm:[1,0,3,2] row_mask:0xf bank_mask:0xf bound_ctrl:1
	s_mov_b32 s13, s12
	v_add_f32_dpp v146, v146, v146 quad_perm:[2,3,0,1] row_mask:0xf bank_mask:0xf bound_ctrl:1
	v_add_f32_dpp v147, v147, v147 quad_perm:[2,3,0,1] row_mask:0xf bank_mask:0xf bound_ctrl:1
	s_and_b32 s5, s2, 12
	v_cndmask_b32_e64 v117, v117, v146, s[12:13]
	v_cndmask_b32_e64 v118, v118, v147, s[12:13]
	s_cmp_lg_u32 s5, 12
	s_cbranch_scc1 .LBB0_597
	v_add_u32_e32 v119, s2, v141
	v_add_u32_e32 v121, 0xffffef00, v116
	v_cndmask_b32_e64 v121, v121, v119, s[6:7]
	v_cndmask_b32_e64 v125, v116, v119, s[6:7]
	v_cmp_gt_i32_e32 vcc, s33, v119
	v_cvt_pk_bf16_f32 v119, v117, v118
	s_nop 0
	v_cndmask_b32_e32 v130, v125, v121, vcc
	v_ashrrev_i32_e32 v131, 31, v130
	v_lshlrev_b64 v[130:131], 10, v[130:131]
	v_lshl_add_u64 v[130:131], v[128:129], 0, v[130:131]
	global_store_dword v[130:131], v119, off
	s_branch .LBB0_597
